# proj GEMM: LDS image in 128-byte rows per k-tile pair so each LDS-DMA load covers 8 rows x full 128B lines (halves address-coalescing work)
# speedup vs baseline: 1.1447x; 1.0371x over previous
.LBB0_116:
	s_or_b64 exec, exec, s[4:5]
	v_readlane_b32 s0, v255, 12
	v_bfe_u32 v0, v166, 4, 2
	v_bfe_u32 v173, v166, 6, 1
	v_bfe_u32 v175, v166, 5, 1
	v_bfe_u32 v1, v166, 2, 2
	s_cmpk_gt_i32 s0, 0xfff
	v_bfe_u32 v177, v166, 2, 4
	v_lshrrev_b32_e32 v172, 7, v166
	v_bitop3_b32 v179, v0, v166, 3 bitop3:0x78
	v_lshlrev_b32_e32 v149, 11, v167
	v_lshlrev_b32_e32 v176, 12, v173
	v_bitop3_b32 v178, v175, v1, 2 bitop3:0x36
	v_lshlrev_b32_e32 v174, 6, v173
	s_barrier
	s_cbranch_scc1 .LBB0_278
	v_lshlrev_b32_e32 v0, 6, v166
	v_and_b32_e32 v0, 0x7c0, v0
	v_bitop3_b32 v2, v175, v148, 3 bitop3:0x78
	s_movk_i32 s0, 0x2000
	v_lshl_or_b32 v1, v172, 12, v0
	v_lshlrev_b32_e32 v2, 4, v2
	v_lshlrev_b32_e32 v3, 4, v178
	v_or3_b32 v0, v176, v0, s0
	v_lshlrev_b32_e32 v135, 3, v179
	v_or_b32_e32 v138, v0, v2
	v_or_b32_e32 v139, v0, v3
	v_lshlrev_b32_e32 v142, 6, v172
	v_mbcnt_lo_u32_b32 v0, -1, 0
	v_lshl_or_b32 v134, v167, 5, v177
	v_or_b32_e32 v136, v1, v2
	v_or_b32_e32 v137, v1, v3
	v_or_b32_e32 v140, 64, v135
	s_movk_i32 s3, 0x60
	v_or_b32_e32 v141, 0x60, v135
	v_or_b32_e32 v143, 1, v142
	v_or_b32_e32 v144, 2, v142
	v_or_b32_e32 v145, 3, v142
	v_or_b32_e32 v146, 8, v142
	v_or_b32_e32 v147, 9, v142
	v_or_b32_e32 v150, 10, v142
	v_or_b32_e32 v151, 11, v142
	v_or_b32_e32 v152, 16, v142
	v_or_b32_e32 v153, 17, v142
	v_or_b32_e32 v154, 18, v142
	v_or_b32_e32 v155, 19, v142
	v_or_b32_e32 v156, 24, v142
	v_or_b32_e32 v157, 25, v142
	v_or_b32_e32 v158, 26, v142
	v_or_b32_e32 v159, 27, v142
	v_or_b32_e32 v160, 32, v142
	v_or_b32_e32 v161, 33, v142
	v_or_b32_e32 v162, 34, v142
	v_or_b32_e32 v163, 35, v142
	v_or_b32_e32 v164, 40, v142
	v_or_b32_e32 v165, 41, v142
	v_or_b32_e32 v180, 42, v142
	v_or_b32_e32 v181, 43, v142
	v_or_b32_e32 v182, 48, v142
	v_or_b32_e32 v183, 49, v142
	v_or_b32_e32 v184, 50, v142
	v_or_b32_e32 v185, 51, v142
	v_or_b32_e32 v186, 56, v142
	v_or_b32_e32 v187, 57, v142
	v_or_b32_e32 v188, 58, v142
	v_or_b32_e32 v189, 59, v142
	v_mov_b32_e32 v129, 0
	v_add_u32_e32 v190, 0x400, v149
	v_add_u32_e32 v191, 0x2000, v149
	v_add_u32_e32 v192, 0x2400, v149
	v_add_u32_e32 v193, 0x4000, v149
	v_add_u32_e32 v194, 0x4400, v149
	v_add_u32_e32 v195, 0x6000, v149
	v_add_u32_e32 v196, 0x6400, v149
	v_add_u32_e32 v197, 0x8000, v149
	v_add_u32_e32 v198, 0x8400, v149
	v_add_u32_e32 v199, 0xa000, v149
	v_add_u32_e32 v200, 0xa400, v149
	v_add_u32_e32 v201, 0xc000, v149
	v_add_u32_e32 v202, 0xc400, v149
	v_add_u32_e32 v203, 0xe000, v149
	v_add_u32_e32 v204, 0xe400, v149
	s_movk_i32 s33, 0x518
	s_movk_i32 s56, 0xf000
	s_movk_i32 s57, 0x1f78
	s_mov_b32 s9, 0
	s_movk_i32 s58, 0x110
	s_movk_i32 s59, 0x3fe8
	s_movk_i32 s60, 0x3ff0
	s_movk_i32 s52, 0x3ff8
	s_movk_i32 s53, 0x3fe0
	v_mbcnt_hi_u32_b32 v205, -1, v0
	v_mov_b32_e32 v206, 0x48
	v_mov_b32_e32 v207, 0x50
	v_mov_b32_e32 v208, 0x58
	v_mov_b32_e32 v209, 0x80
	v_mov_b32_e32 v210, 0x88
	v_mov_b32_e32 v211, 0x90
	v_mov_b32_e32 v212, 0x98
	v_mov_b32_e32 v213, 0xc0
	v_mov_b32_e32 v214, 0xc8
	v_mov_b32_e32 v215, 0xd0
	v_mov_b32_e32 v216, 0xd8
	v_mov_b32_e32 v217, 0x100
	v_mov_b32_e32 v218, 0x108
	v_mov_b32_e32 v219, 0x110
	v_mov_b32_e32 v220, 0x118
	v_mov_b32_e32 v221, 0x140
	v_mov_b32_e32 v222, 0x148
	v_mov_b32_e32 v223, 0x150
	v_mov_b32_e32 v224, 0x158
	v_mov_b32_e32 v225, 0x180
	v_mov_b32_e32 v226, 0x188
	v_mov_b32_e32 v227, 0x190
	v_mov_b32_e32 v228, 0x198
	v_mov_b32_e32 v229, 0x1c0
	v_mov_b32_e32 v230, 0x1c8
	v_mov_b32_e32 v231, 0x1d0
	v_readlane_b32 s54, v255, 12
	v_lshrrev_b32_e32 v0, 3, v253
	v_and_b32_e32 v1, 7, v253
	v_bfe_u32 v2, v253, 4, 2
	v_xor_b32_e32 v1, v1, v2
	v_lshlrev_b32_e32 v200, 3, v1
	v_xor_b32_e32 v1, 4, v1
	v_lshlrev_b32_e32 v201, 3, v1
	v_lshl_or_b32 v198, v167, 5, v0
	v_and_b32_e32 v0, 15, v253
	v_bfe_u32 v1, v253, 4, 1
	v_lshl_or_b32 v0, v1, 4, v0
	v_lshl_or_b32 v1, v172, 6, v0
	v_lshl_or_b32 v2, v173, 6, v0
	v_lshlrev_b32_e32 v1, 7, v1
	v_lshlrev_b32_e32 v2, 7, v2
	v_add_u32_e32 v2, 0x4000, v2
	v_bfe_u32 v3, v253, 1, 3
	v_lshrrev_b32_e32 v4, 5, v253
	v_mov_b32_e32 v5, v4
	v_xor_b32_e32 v5, v5, v3
	v_lshl_add_u32 v136, v5, 4, v1
	v_or_b32_e32 v5, 2, v4
	v_xor_b32_e32 v5, v5, v3
	v_lshl_add_u32 v137, v5, 4, v1
	v_mov_b32_e32 v5, v4
	v_xor_b32_e32 v5, v5, v3
	v_lshl_add_u32 v138, v5, 4, v2
	v_or_b32_e32 v5, 2, v4
	v_xor_b32_e32 v5, v5, v3
	v_lshl_add_u32 v139, v5, 4, v2
	v_or_b32_e32 v5, 4, v4
	v_xor_b32_e32 v5, v5, v3
	v_lshl_add_u32 v192, v5, 4, v1
	v_or_b32_e32 v5, 6, v4
	v_xor_b32_e32 v5, v5, v3
	v_lshl_add_u32 v193, v5, 4, v1
	v_or_b32_e32 v5, 4, v4
	v_xor_b32_e32 v5, v5, v3
	v_lshl_add_u32 v194, v5, 4, v2
	v_or_b32_e32 v5, 6, v4
	v_xor_b32_e32 v5, v5, v3
	v_lshl_add_u32 v195, v5, 4, v2
	s_branch .LBB0_119

.LBB0_119:
	s_ashr_i32 s8, s54, 5
	s_lshr_b32 s98, s54, 9
	s_lshl2_add_u32 s98, s98, s54
	s_and_b32 s11, s98, 31
	s_lshl_b32 s55, s8, 7
	s_lshl_b32 s10, s11, 7
	v_add_u32_e32 v0, s55, v198
	s_movk_i32 s0, 0x440
	v_mul_lo_u32 v8, v0, s0
	v_add_u32_e32 v0, s10, v198
	v_mul_lo_u32 v9, v0, s0
	v_add_u32_e32 v132, v8, v200
	v_add_u32_e32 v196, v8, v201
	v_add_u32_e32 v130, v9, v200
	v_add_u32_e32 v197, v9, v201
	v_mov_b32_e32 v133, v129
	v_mov_b32_e32 v131, v129
	s_waitcnt vmcnt(0)
	v_readfirstlane_b32 s2, v149
	v_readlane_b32 s48, v255, 57
	v_readlane_b32 s49, v255, 58
	s_lshl_b32 s2, s2, 1
	v_add_u32_e32 v128, 0x0, v132
	s_add_u32 m0, s2, 0x0
	v_lshl_add_u64 v[0:1], v[128:129], 1, s[90:91]
	global_load_lds_dwordx4 v[0:1], off
	v_add_u32_e32 v128, 0x2200, v196
	s_add_u32 m0, s2, 0x400
	v_lshl_add_u64 v[0:1], v[128:129], 1, s[90:91]
	global_load_lds_dwordx4 v[0:1], off
	v_add_u32_e32 v128, 0x4400, v132
	s_add_u32 m0, s2, 0x800
	v_lshl_add_u64 v[0:1], v[128:129], 1, s[90:91]
	global_load_lds_dwordx4 v[0:1], off
	v_add_u32_e32 v128, 0x6600, v196
	s_add_u32 m0, s2, 0xc00
	v_lshl_add_u64 v[0:1], v[128:129], 1, s[90:91]
	global_load_lds_dwordx4 v[0:1], off
	v_add_u32_e32 v128, 0x0, v130
	s_add_u32 m0, s2, 0x4000
	v_lshl_add_u64 v[0:1], v[128:129], 1, s[48:49]
	global_load_lds_dwordx4 v[0:1], off
	v_add_u32_e32 v128, 0x2200, v197
	s_add_u32 m0, s2, 0x4400
	v_lshl_add_u64 v[0:1], v[128:129], 1, s[48:49]
	global_load_lds_dwordx4 v[0:1], off
	v_add_u32_e32 v128, 0x4400, v130
	s_add_u32 m0, s2, 0x4800
	v_lshl_add_u64 v[0:1], v[128:129], 1, s[48:49]
	global_load_lds_dwordx4 v[0:1], off
	v_add_u32_e32 v128, 0x6600, v197
	s_add_u32 m0, s2, 0x4c00
	v_lshl_add_u64 v[0:1], v[128:129], 1, s[48:49]
	global_load_lds_dwordx4 v[0:1], off
	v_readfirstlane_b32 s2, v149
	v_readlane_b32 s48, v255, 57
	v_readlane_b32 s49, v255, 58
	s_lshl_b32 s2, s2, 1
	v_add_u32_e32 v128, 0x40, v132
	s_add_u32 m0, s2, 0x8000
	v_lshl_add_u64 v[0:1], v[128:129], 1, s[90:91]
	global_load_lds_dwordx4 v[0:1], off
	v_add_u32_e32 v128, 0x2240, v196
	s_add_u32 m0, s2, 0x8400
	v_lshl_add_u64 v[0:1], v[128:129], 1, s[90:91]
	global_load_lds_dwordx4 v[0:1], off
	v_add_u32_e32 v128, 0x4440, v132
	s_add_u32 m0, s2, 0x8800
	v_lshl_add_u64 v[0:1], v[128:129], 1, s[90:91]
	global_load_lds_dwordx4 v[0:1], off
	v_add_u32_e32 v128, 0x6640, v196
	s_add_u32 m0, s2, 0x8c00
	v_lshl_add_u64 v[0:1], v[128:129], 1, s[90:91]
	global_load_lds_dwordx4 v[0:1], off
	v_add_u32_e32 v128, 0x40, v130
	s_add_u32 m0, s2, 0xc000
	v_lshl_add_u64 v[0:1], v[128:129], 1, s[48:49]
	global_load_lds_dwordx4 v[0:1], off
	v_add_u32_e32 v128, 0x2240, v197
	s_add_u32 m0, s2, 0xc400
	v_lshl_add_u64 v[0:1], v[128:129], 1, s[48:49]
	global_load_lds_dwordx4 v[0:1], off
	v_add_u32_e32 v128, 0x4440, v130
	s_add_u32 m0, s2, 0xc800
	v_lshl_add_u64 v[0:1], v[128:129], 1, s[48:49]
	global_load_lds_dwordx4 v[0:1], off
	v_add_u32_e32 v128, 0x6640, v197
	s_add_u32 m0, s2, 0xcc00
	v_lshl_add_u64 v[0:1], v[128:129], 1, s[48:49]
	global_load_lds_dwordx4 v[0:1], off
	s_waitcnt vmcnt(8)
	s_waitcnt lgkmcnt(0)
	s_barrier
	s_mov_b32 s0, 0
	s_mov_b32 s1, 0
	v_mov_b32_e32 v0, v129
	v_mov_b32_e32 v1, v129
	v_mov_b32_e32 v2, v129
	v_mov_b32_e32 v3, v129
	v_mov_b32_e32 v4, v129
	v_mov_b32_e32 v5, v129
	v_mov_b32_e32 v6, v129
	v_mov_b32_e32 v7, v129
	v_mov_b32_e32 v8, v129
	v_mov_b32_e32 v9, v129
	v_mov_b32_e32 v10, v129
	v_mov_b32_e32 v11, v129
	v_mov_b32_e32 v12, v129
	v_mov_b32_e32 v13, v129
	v_mov_b32_e32 v14, v129
	v_mov_b32_e32 v15, v129
	v_mov_b32_e32 v16, v129
	v_mov_b32_e32 v17, v129
	v_mov_b32_e32 v18, v129
	v_mov_b32_e32 v19, v129
	v_mov_b32_e32 v20, v129
	v_mov_b32_e32 v21, v129
	v_mov_b32_e32 v22, v129
	v_mov_b32_e32 v23, v129
	v_mov_b32_e32 v24, v129
	v_mov_b32_e32 v25, v129
	v_mov_b32_e32 v26, v129
	v_mov_b32_e32 v27, v129
	v_mov_b32_e32 v28, v129
	v_mov_b32_e32 v29, v129
	v_mov_b32_e32 v30, v129
	v_mov_b32_e32 v31, v129
	v_mov_b32_e32 v32, v129
	v_mov_b32_e32 v33, v129
	v_mov_b32_e32 v34, v129
	v_mov_b32_e32 v35, v129
	v_mov_b32_e32 v36, v129
	v_mov_b32_e32 v37, v129
	v_mov_b32_e32 v38, v129
	v_mov_b32_e32 v39, v129
	v_mov_b32_e32 v40, v129
	v_mov_b32_e32 v41, v129
	v_mov_b32_e32 v42, v129
	v_mov_b32_e32 v43, v129
	v_mov_b32_e32 v44, v129
	v_mov_b32_e32 v45, v129
	v_mov_b32_e32 v46, v129
	v_mov_b32_e32 v47, v129
	v_mov_b32_e32 v48, v129
	v_mov_b32_e32 v49, v129
	v_mov_b32_e32 v50, v129
	v_mov_b32_e32 v51, v129
	v_mov_b32_e32 v52, v129
	v_mov_b32_e32 v53, v129
	v_mov_b32_e32 v54, v129
	v_mov_b32_e32 v55, v129
	v_mov_b32_e32 v56, v129
	v_mov_b32_e32 v57, v129
	v_mov_b32_e32 v58, v129
	v_mov_b32_e32 v59, v129
	v_mov_b32_e32 v60, v129
	v_mov_b32_e32 v61, v129
	v_mov_b32_e32 v62, v129
	v_mov_b32_e32 v63, v129
	v_readlane_b32 s37, v255, 46
	v_readlane_b32 s38, v255, 47
	v_readlane_b32 s39, v255, 48
	v_readlane_b32 s40, v255, 49
	v_readlane_b32 s41, v255, 50
	v_readlane_b32 s42, v255, 51
	v_readlane_b32 s43, v255, 52
	v_readlane_b32 s44, v255, 53
	v_readlane_b32 s45, v255, 54
	v_readlane_b32 s46, v255, 55
	v_readlane_b32 s47, v255, 56
	v_readlane_b32 s50, v255, 59
	v_readlane_b32 s51, v255, 60
	ds_read_b128 v[64:67], v136 offset:0x0
	ds_read_b128 v[68:71], v136 offset:0x1000
	ds_read_b128 v[76:79], v138 offset:0x0
	ds_read_b128 v[80:83], v138 offset:0x1000
	ds_read_b128 v[84:87], v137 offset:0x0
	ds_read_b128 v[72:75], v137 offset:0x1000
	ds_read_b128 v[92:95], v139 offset:0x0
	ds_read_b128 v[88:91], v139 offset:0x1000
	s_branch .LBB0_122
.LBB0_120:
	ds_read_b128 v[64:67], v136 offset:0x0
	ds_read_b128 v[68:71], v136 offset:0x1000
	ds_read_b128 v[76:79], v138 offset:0x0
	ds_read_b128 v[80:83], v138 offset:0x1000
	ds_read_b128 v[84:87], v137 offset:0x0
	ds_read_b128 v[72:75], v137 offset:0x1000
	ds_read_b128 v[92:95], v139 offset:0x0
	ds_read_b128 v[88:91], v139 offset:0x1000

.LBB0_124:
	v_mfma_f32_32x32x16_bf16 v[48:63], v[64:67], v[76:79], v[48:63]
	s_mov_b64 s[6:7], -1
	s_and_b64 vcc, exec, s[4:5]
	v_mfma_f32_32x32x16_bf16 v[32:47], v[64:67], v[80:83], v[32:47]
	v_mfma_f32_32x32x16_bf16 v[16:31], v[68:71], v[76:79], v[16:31]
	ds_read_b128 v[76:79], v192 offset:0x0
	ds_read_b128 v[64:67], v192 offset:0x1000
	v_mfma_f32_32x32x16_bf16 v[0:15], v[68:71], v[80:83], v[0:15]
	v_mfma_f32_32x32x16_bf16 v[48:63], v[84:87], v[92:95], v[48:63]
	v_mfma_f32_32x32x16_bf16 v[32:47], v[84:87], v[88:91], v[32:47]
	ds_read_b128 v[84:87], v194 offset:0x0
	v_mfma_f32_32x32x16_bf16 v[16:31], v[72:75], v[92:95], v[16:31]
	ds_read_b128 v[92:95], v194 offset:0x1000
	ds_read_b128 v[68:71], v193 offset:0x0
	ds_read_b128 v[96:99], v193 offset:0x1000
	ds_read_b128 v[80:83], v195 offset:0x0
	ds_read_b128 v[100:103], v195 offset:0x1000
	v_mfma_f32_32x32x16_bf16 v[0:15], v[72:75], v[88:91], v[0:15]
	s_waitcnt vmcnt(0)
.LBB0_132:
	s_waitcnt lgkmcnt(0)
	s_cmp_gt_u32 s1, 26
	s_cselect_b64 s[6:7], -1, 0
	s_and_b64 vcc, exec, s[6:7]
	s_barrier
	s_cbranch_vccnz .LBB0_134
	v_readfirstlane_b32 s2, v149
	v_readlane_b32 s48, v255, 57
	v_readlane_b32 s49, v255, 58
	s_lshl_b32 s2, s2, 1
	s_add_u32 s99, s0, 0x80
	v_add_u32_e32 v128, s99, v132
	s_add_u32 m0, s2, 0x0
	v_lshl_add_u64 v[72:73], v[128:129], 1, s[90:91]
	global_load_lds_dwordx4 v[72:73], off
	s_add_u32 s99, s0, 0x2280
	v_add_u32_e32 v128, s99, v196
	s_add_u32 m0, s2, 0x400
	v_lshl_add_u64 v[72:73], v[128:129], 1, s[90:91]
	global_load_lds_dwordx4 v[72:73], off
	s_add_u32 s99, s0, 0x4480
	v_add_u32_e32 v128, s99, v132
	s_add_u32 m0, s2, 0x800
	v_lshl_add_u64 v[72:73], v[128:129], 1, s[90:91]
	global_load_lds_dwordx4 v[72:73], off
	s_add_u32 s99, s0, 0x6680
	v_add_u32_e32 v128, s99, v196
	s_add_u32 m0, s2, 0xc00
	v_lshl_add_u64 v[72:73], v[128:129], 1, s[90:91]
	global_load_lds_dwordx4 v[72:73], off
	s_add_u32 s99, s0, 0x80
	v_add_u32_e32 v128, s99, v130
	s_add_u32 m0, s2, 0x4000
	v_lshl_add_u64 v[72:73], v[128:129], 1, s[48:49]
	global_load_lds_dwordx4 v[72:73], off
	s_add_u32 s99, s0, 0x2280
	v_add_u32_e32 v128, s99, v197
	s_add_u32 m0, s2, 0x4400
	v_lshl_add_u64 v[72:73], v[128:129], 1, s[48:49]
	global_load_lds_dwordx4 v[72:73], off
	s_add_u32 s99, s0, 0x4480
	v_add_u32_e32 v128, s99, v130
	s_add_u32 m0, s2, 0x4800
	v_lshl_add_u64 v[72:73], v[128:129], 1, s[48:49]
	global_load_lds_dwordx4 v[72:73], off
	s_add_u32 s99, s0, 0x6680
	v_add_u32_e32 v128, s99, v197
	s_add_u32 m0, s2, 0x4c00
	v_lshl_add_u64 v[72:73], v[128:129], 1, s[48:49]
	global_load_lds_dwordx4 v[72:73], off
.LBB0_134:
	v_mfma_f32_32x32x16_bf16 v[48:63], v[76:79], v[84:87], v[48:63]
	s_mov_b64 s[28:29], -1
	s_and_b64 vcc, exec, s[6:7]
	v_mfma_f32_32x32x16_bf16 v[32:47], v[76:79], v[92:95], v[32:47]
	v_mfma_f32_32x32x16_bf16 v[16:31], v[64:67], v[84:87], v[16:31]
	v_mfma_f32_32x32x16_bf16 v[0:15], v[64:67], v[92:95], v[0:15]
	ds_read_b128 v[64:67], v136 offset:0x8000
	v_mfma_f32_32x32x16_bf16 v[48:63], v[68:71], v[80:83], v[48:63]
	v_mfma_f32_32x32x16_bf16 v[32:47], v[68:71], v[100:103], v[32:47]
	ds_read_b128 v[68:71], v136 offset:0x9000
	ds_read_b128 v[76:79], v138 offset:0x8000
	v_mfma_f32_32x32x16_bf16 v[16:31], v[96:99], v[80:83], v[16:31]
	ds_read_b128 v[80:83], v138 offset:0x9000
	ds_read_b128 v[84:87], v137 offset:0x8000
	ds_read_b128 v[72:75], v137 offset:0x9000
	ds_read_b128 v[92:95], v139 offset:0x8000
	ds_read_b128 v[88:91], v139 offset:0x9000
	v_mfma_f32_32x32x16_bf16 v[0:15], v[96:99], v[100:103], v[0:15]
	s_cbranch_vccz .LBB0_136
	s_waitcnt vmcnt(0)
	s_mov_b64 s[28:29], 0

.LBB0_140:
	v_mfma_f32_32x32x16_bf16 v[48:63], v[64:67], v[76:79], v[48:63]
	s_mov_b64 s[28:29], -1
	s_and_b64 vcc, exec, s[4:5]
	ds_read_b128 v[116:119], v192 offset:0x8000
	ds_read_b128 v[104:107], v192 offset:0x9000
	ds_read_b128 v[120:123], v194 offset:0x8000
	ds_read_b128 v[124:127], v194 offset:0x9000
	ds_read_b128 v[108:111], v193 offset:0x8000
	v_mfma_f32_32x32x16_bf16 v[32:47], v[64:67], v[80:83], v[32:47]
	ds_read_b128 v[96:99], v193 offset:0x9000
	ds_read_b128 v[112:115], v195 offset:0x8000
	ds_read_b128 v[100:103], v195 offset:0x9000
	v_mfma_f32_32x32x16_bf16 v[16:31], v[68:71], v[76:79], v[16:31]
	v_mfma_f32_32x32x16_bf16 v[0:15], v[68:71], v[80:83], v[0:15]
	v_mfma_f32_32x32x16_bf16 v[48:63], v[84:87], v[92:95], v[48:63]
	v_mfma_f32_32x32x16_bf16 v[32:47], v[84:87], v[88:91], v[32:47]
	v_mfma_f32_32x32x16_bf16 v[16:31], v[72:75], v[92:95], v[16:31]
	v_mfma_f32_32x32x16_bf16 v[0:15], v[72:75], v[88:91], v[0:15]
	s_cbranch_vccz .LBB0_142
	s_waitcnt lgkmcnt(0)
	s_mov_b64 s[28:29], 0
.LBB0_142:
	s_andn2_b64 vcc, exec, s[28:29]
	s_cbranch_vccnz .LBB0_121
	s_waitcnt vmcnt(0)
.LBB0_147:
	s_waitcnt lgkmcnt(0)
	s_cmp_gt_u32 s1, 24
	s_barrier
	s_cbranch_scc1 .LBB0_120
	v_readfirstlane_b32 s2, v149
	v_readlane_b32 s48, v255, 57
	v_readlane_b32 s49, v255, 58
	s_lshl_b32 s2, s2, 1
	s_add_u32 s99, s0, 0xc0
	v_add_u32_e32 v128, s99, v132
	s_add_u32 m0, s2, 0x8000
	v_lshl_add_u64 v[64:65], v[128:129], 1, s[90:91]
	global_load_lds_dwordx4 v[64:65], off
	s_add_u32 s99, s0, 0x22c0
	v_add_u32_e32 v128, s99, v196
	s_add_u32 m0, s2, 0x8400
	v_lshl_add_u64 v[64:65], v[128:129], 1, s[90:91]
	global_load_lds_dwordx4 v[64:65], off
	s_add_u32 s99, s0, 0x44c0
	v_add_u32_e32 v128, s99, v132
	s_add_u32 m0, s2, 0x8800
	v_lshl_add_u64 v[64:65], v[128:129], 1, s[90:91]
	global_load_lds_dwordx4 v[64:65], off
	s_add_u32 s99, s0, 0x66c0
	v_add_u32_e32 v128, s99, v196
	s_add_u32 m0, s2, 0x8c00
	v_lshl_add_u64 v[64:65], v[128:129], 1, s[90:91]
	global_load_lds_dwordx4 v[64:65], off
	s_add_u32 s99, s0, 0xc0
	v_add_u32_e32 v128, s99, v130
	s_add_u32 m0, s2, 0xc000
	v_lshl_add_u64 v[64:65], v[128:129], 1, s[48:49]
	global_load_lds_dwordx4 v[64:65], off
	s_add_u32 s99, s0, 0x22c0
	v_add_u32_e32 v128, s99, v197
	s_add_u32 m0, s2, 0xc400
	v_lshl_add_u64 v[64:65], v[128:129], 1, s[48:49]
	global_load_lds_dwordx4 v[64:65], off
	s_add_u32 s99, s0, 0x44c0
	v_add_u32_e32 v128, s99, v130
	s_add_u32 m0, s2, 0xc800
	v_lshl_add_u64 v[64:65], v[128:129], 1, s[48:49]
	global_load_lds_dwordx4 v[64:65], off
	s_add_u32 s99, s0, 0x66c0
	v_add_u32_e32 v128, s99, v197
	s_add_u32 m0, s2, 0xcc00
	v_lshl_add_u64 v[64:65], v[128:129], 1, s[48:49]
	global_load_lds_dwordx4 v[64:65], off
	s_branch .LBB0_120
